# P9 bundle: redundant canonicalising v_max before the clamp dropped in the gated-DeltaNet scan, mLSTM quad shuffles via DPP, MoBA setup loads batched
# baseline (speedup 1.0000x reference)
.Lscan_pfA_skip:
	s_mov_b32 s0, 0x358637bd
	ds_read_b128 v[108:111], v116 offset:46080
	ds_read_b128 v[240:243], v117
	ds_read_b128 v[244:247], v117 offset:2304
	ds_read_b128 v[252:255], v117 offset:4608
	s_waitcnt lgkmcnt(2)
	v_mfma_f32_16x16x32_f16 v[236:239], v[108:111], v[240:243], 0
	ds_read_b128 v[240:243], v117 offset:6912
	ds_read_b128 v[174:177], v116 offset:46144
	s_waitcnt lgkmcnt(3)
	v_mfma_f32_16x16x32_f16 v[104:107], v[108:111], v[244:247], 0
	ds_read_b128 v[244:247], v117 offset:64
	s_waitcnt lgkmcnt(3)
	v_mfma_f32_16x16x32_f16 v[100:103], v[108:111], v[252:255], 0
	ds_read_b128 v[252:255], v117 offset:2368
	s_waitcnt lgkmcnt(3)
	v_mfma_f32_16x16x32_f16 v[96:99], v[108:111], v[240:243], 0
	ds_read_b128 v[240:243], v117 offset:4672
	s_waitcnt lgkmcnt(2)
	v_mfma_f32_16x16x32_f16 v[236:239], v[174:177], v[244:247], v[236:239]
	ds_read_b128 v[244:247], v117 offset:6976
	s_waitcnt lgkmcnt(2)
	v_mfma_f32_16x16x32_f16 v[104:107], v[174:177], v[252:255], v[104:107]
	s_waitcnt lgkmcnt(1)
	v_mfma_f32_16x16x32_f16 v[100:103], v[174:177], v[240:243], v[100:103]
	s_waitcnt lgkmcnt(0)
	v_mfma_f32_16x16x32_f16 v[96:99], v[174:177], v[244:247], v[96:99]
	ds_read_b64 v[108:109], v214 offset:9216
	s_waitcnt lgkmcnt(0)
	v_cvt_f32_f16_e32 v110, v108
	v_cvt_f32_f16_sdwa v108, v108 dst_sel:DWORD dst_unused:UNUSED_PAD src0_sel:WORD_1
	v_sub_f32_e32 v110, v110, v236
	v_sub_f32_e32 v108, v108, v237
	v_med3_f32 v108, v108, s57, v194
	v_cvt_f16_f32_e32 v108, v108
	v_med3_f32 v110, v110, s57, v194
	v_cvt_f16_f32_e32 v110, v110
	ds_write_b16 v215, v108 offset:55440
	v_cvt_f32_f16_e32 v108, v109
	ds_write_b16 v215, v110 offset:55296
	v_sub_f32_e32 v108, v108, v238
	v_med3_f32 v108, v108, s57, v194
	v_cvt_f16_f32_e32 v108, v108
	ds_write_b16 v215, v108 offset:55584
	v_cvt_f32_f16_sdwa v108, v109 dst_sel:DWORD dst_unused:UNUSED_PAD src0_sel:WORD_1
	v_sub_f32_e32 v108, v108, v239
	v_med3_f32 v108, v108, s57, v194
	v_cvt_f16_f32_e32 v108, v108
	ds_write_b16 v215, v108 offset:55728
	ds_read_b64 v[108:109], v214 offset:11520
	s_waitcnt lgkmcnt(0)
	v_cvt_f32_f16_e32 v110, v108
	v_sub_f32_e32 v104, v110, v104
	v_med3_f32 v104, v104, s57, v194
	v_cvt_f16_f32_e32 v104, v104
	ds_write_b16 v215, v104 offset:55328
	v_cvt_f32_f16_sdwa v104, v108 dst_sel:DWORD dst_unused:UNUSED_PAD src0_sel:WORD_1
	v_sub_f32_e32 v104, v104, v105
	v_med3_f32 v104, v104, s57, v194
	v_cvt_f16_f32_e32 v104, v104
	ds_write_b16 v216, v104 offset:55440
	v_cvt_f32_f16_e32 v104, v109
	v_sub_f32_e32 v104, v104, v106
	v_med3_f32 v104, v104, s57, v194
	v_cvt_f16_f32_e32 v104, v104
	ds_write_b16 v216, v104 offset:55584
	v_cvt_f32_f16_sdwa v104, v109 dst_sel:DWORD dst_unused:UNUSED_PAD src0_sel:WORD_1
	v_sub_f32_e32 v104, v104, v107
	v_med3_f32 v104, v104, s57, v194
	v_cvt_f16_f32_e32 v104, v104
	ds_write_b16 v216, v104 offset:55728
	ds_read_b64 v[104:105], v214 offset:13824
	s_waitcnt lgkmcnt(0)
	v_cvt_f32_f16_e32 v106, v104
	v_sub_f32_e32 v100, v106, v100
	v_med3_f32 v100, v100, s57, v194
	v_cvt_f16_f32_e32 v100, v100
	ds_write_b16 v215, v100 offset:55360
	v_cvt_f32_f16_sdwa v100, v104 dst_sel:DWORD dst_unused:UNUSED_PAD src0_sel:WORD_1
	v_sub_f32_e32 v100, v100, v101
	v_med3_f32 v100, v100, s57, v194
	v_cvt_f16_f32_e32 v100, v100
	ds_write_b16 v217, v100 offset:55440
	v_cvt_f32_f16_e32 v100, v105
	v_sub_f32_e32 v100, v100, v102
	v_med3_f32 v100, v100, s57, v194
	v_cvt_f16_f32_e32 v100, v100
	ds_write_b16 v217, v100 offset:55584
	v_cvt_f32_f16_sdwa v100, v105 dst_sel:DWORD dst_unused:UNUSED_PAD src0_sel:WORD_1
	v_sub_f32_e32 v100, v100, v103
	v_med3_f32 v100, v100, s57, v194
	v_cvt_f16_f32_e32 v100, v100
	ds_write_b16 v217, v100 offset:55728
	ds_read_b64 v[100:101], v214 offset:16128
	s_waitcnt lgkmcnt(0)
	v_cvt_f32_f16_e32 v102, v100
	v_sub_f32_e32 v96, v102, v96
	v_med3_f32 v96, v96, s57, v194
	v_cvt_f16_f32_e32 v96, v96
	ds_write_b16 v215, v96 offset:55392
	v_cvt_f32_f16_sdwa v96, v100 dst_sel:DWORD dst_unused:UNUSED_PAD src0_sel:WORD_1
	v_sub_f32_e32 v96, v96, v97
	v_med3_f32 v96, v96, s57, v194
	v_cvt_f16_f32_e32 v96, v96
	ds_write_b16 v218, v96 offset:55440
	v_cvt_f32_f16_e32 v96, v101
	v_sub_f32_e32 v96, v96, v98
	v_med3_f32 v96, v96, s57, v194
	v_cvt_f16_f32_e32 v96, v96
	ds_write_b16 v218, v96 offset:55584
	v_cvt_f32_f16_sdwa v96, v101 dst_sel:DWORD dst_unused:UNUSED_PAD src0_sel:WORD_1
	v_sub_f32_e32 v96, v96, v99
	v_med3_f32 v96, v96, s57, v194
	v_cvt_f16_f32_e32 v96, v96
	ds_write_b16 v218, v96 offset:55728
	s_waitcnt lgkmcnt(0)
	s_barrier
	ds_write_b128 v115, v[0:3]
	ds_write_b128 v209, v[4:7]
	ds_write_b128 v219, v[8:11]
	ds_write_b128 v210, v[12:15]
	s_waitcnt vmcnt(15)
	v_cvt_f32_f16_e32 v235, v234
	global_load_dword v234, v[118:119], off
	ds_read_b128 v[174:177], v116 offset:27648
	ds_read_b128 v[240:243], v117 offset:46080
	ds_read_b128 v[244:247], v117 offset:48384
	ds_read_b128 v[252:255], v117 offset:50688
	s_waitcnt lgkmcnt(2)
	v_mfma_f32_16x16x32_f16 v[108:111], v[174:177], v[240:243], 0
	ds_read_b128 v[240:243], v117 offset:52992
	ds_read_b128 v[236:239], v116 offset:27712
	s_waitcnt lgkmcnt(3)
	v_mfma_f32_16x16x32_f16 v[104:107], v[174:177], v[244:247], 0
	ds_read_b128 v[244:247], v117 offset:46144
	s_waitcnt lgkmcnt(3)
	v_mfma_f32_16x16x32_f16 v[100:103], v[174:177], v[252:255], 0
	ds_read_b128 v[252:255], v117 offset:48448
	s_waitcnt lgkmcnt(3)
	v_mfma_f32_16x16x32_f16 v[96:99], v[174:177], v[240:243], 0
	ds_read_b128 v[240:243], v117 offset:50752
	s_waitcnt lgkmcnt(2)
	v_mfma_f32_16x16x32_f16 v[108:111], v[236:239], v[244:247], v[108:111]
	ds_read_b128 v[244:247], v117 offset:53056
	ds_read_b128 v[174:177], v116 offset:18432
	s_waitcnt lgkmcnt(3)
	v_mfma_f32_16x16x32_f16 v[104:107], v[236:239], v[252:255], v[104:107]
	ds_read_b128 v[252:255], v117 offset:55296
	s_waitcnt lgkmcnt(3)
	v_mfma_f32_16x16x32_f16 v[100:103], v[236:239], v[240:243], v[100:103]
	ds_read_b128 v[240:243], v117 offset:57600
	s_waitcnt lgkmcnt(3)
	v_mfma_f32_16x16x32_f16 v[96:99], v[236:239], v[244:247], v[96:99]
	ds_read_b128 v[244:247], v117 offset:59904
	s_waitcnt lgkmcnt(2)
	v_mfma_f32_16x16x32_f16 v[108:111], v[174:177], v[252:255], v[108:111]
	ds_read_b128 v[252:255], v117 offset:62208
	ds_read_b128 v[236:239], v116 offset:18496
	s_waitcnt lgkmcnt(3)
	v_mfma_f32_16x16x32_f16 v[104:107], v[174:177], v[240:243], v[104:107]
	ds_read_b128 v[240:243], v117 offset:55360
	s_waitcnt lgkmcnt(3)
	v_mfma_f32_16x16x32_f16 v[100:103], v[174:177], v[244:247], v[100:103]
	ds_read_b128 v[244:247], v117 offset:57664
	s_waitcnt lgkmcnt(3)
	v_mfma_f32_16x16x32_f16 v[96:99], v[174:177], v[252:255], v[96:99]
	ds_read_b128 v[252:255], v117 offset:59968
	s_waitcnt lgkmcnt(2)
	v_mfma_f32_16x16x32_f16 v[108:111], v[236:239], v[240:243], v[108:111]
	ds_read_b128 v[240:243], v117 offset:62272
	s_waitcnt lgkmcnt(2)
	v_mfma_f32_16x16x32_f16 v[104:107], v[236:239], v[244:247], v[104:107]
	s_waitcnt lgkmcnt(1)
	v_mfma_f32_16x16x32_f16 v[100:103], v[236:239], v[252:255], v[100:103]
	s_waitcnt lgkmcnt(0)
	v_mfma_f32_16x16x32_f16 v[96:99], v[236:239], v[240:243], v[96:99]
	v_mul_f32_e32 v236, 0xbfb8aa3b, v235
	v_exp_f32_e32 v236, v236
	v_mov_b32_e32 v174, v108
	v_mov_b32_e32 v175, v104
	v_pk_mul_f32 v[176:177], v[174:175], v[174:175]
	v_add_f32_e32 v236, 1.0, v236
	v_div_scale_f32 v237, s[8:9], v236, v236, v235
	v_rcp_f32_e32 v238, v237
	v_mov_b32_e32 v174, v100
	v_mov_b32_e32 v175, v96
	v_pk_mul_f32 v[174:175], v[174:175], v[174:175]
	v_fma_f32 v239, -v237, v238, 1.0
	v_fmac_f32_e32 v238, v239, v238
	v_div_scale_f32 v239, vcc, v235, v236, v235
	v_mul_f32_e32 v240, v239, v238
	v_fma_f32 v241, -v237, v240, v239
	v_fmac_f32_e32 v240, v241, v238
	v_fma_f32 v237, -v237, v240, v239
	v_div_fmas_f32 v237, v237, v238, v240
	v_div_fixup_f32 v235, v237, v236, v235
	s_waitcnt vmcnt(15)
	v_cvt_f32_f16_e32 v236, v233
	global_load_dword v233, v[118:119], off offset:64
	v_mul_f32_e32 v237, 0xbfb8aa3b, v236
	v_exp_f32_e32 v237, v237
	s_nop 0
	v_add_f32_e32 v237, 1.0, v237
	v_div_scale_f32 v238, s[8:9], v237, v237, v236
	v_rcp_f32_e32 v239, v238
	s_nop 0
	v_fma_f32 v240, -v238, v239, 1.0
	v_fmac_f32_e32 v239, v240, v239
	v_div_scale_f32 v240, vcc, v236, v237, v236
	v_mul_f32_e32 v241, v240, v239
	v_fma_f32 v242, -v238, v241, v240
	v_fmac_f32_e32 v241, v242, v239
	v_fma_f32 v238, -v238, v241, v240
	v_div_fmas_f32 v238, v238, v239, v241
	v_div_fixup_f32 v242, v238, v237, v236
	s_waitcnt vmcnt(15)
	v_cvt_f32_f16_e32 v236, v232
	global_load_dword v232, v[118:119], off offset:128
	v_mul_f32_e32 v237, 0xbfb8aa3b, v236
	v_exp_f32_e32 v237, v237
	s_nop 0
	v_add_f32_e32 v237, 1.0, v237
	v_div_scale_f32 v238, s[8:9], v237, v237, v236
	v_rcp_f32_e32 v239, v238
	s_nop 0
	v_fma_f32 v240, -v238, v239, 1.0
	v_fmac_f32_e32 v239, v240, v239
	v_div_scale_f32 v240, vcc, v236, v237, v236
	v_mul_f32_e32 v241, v240, v239
	v_fma_f32 v243, -v238, v241, v240
	v_fmac_f32_e32 v241, v243, v239
	v_fma_f32 v238, -v238, v241, v240
	v_div_fmas_f32 v238, v238, v239, v241
	v_div_fixup_f32 v243, v238, v237, v236
	s_waitcnt vmcnt(15)
	v_cvt_f32_f16_e32 v236, v231
	global_load_dword v231, v[118:119], off offset:192
	v_mul_f32_e32 v237, 0xbfb8aa3b, v236
	v_exp_f32_e32 v237, v237
	s_nop 0
	v_add_f32_e32 v237, 1.0, v237
	v_div_scale_f32 v238, s[8:9], v237, v237, v236
	v_rcp_f32_e32 v239, v238
	s_nop 0
	v_fma_f32 v240, -v238, v239, 1.0
	v_fmac_f32_e32 v239, v240, v239
	v_div_scale_f32 v240, vcc, v236, v237, v236
	v_mul_f32_e32 v241, v240, v239
	v_fma_f32 v244, -v238, v241, v240
	v_fmac_f32_e32 v241, v244, v239
	v_fma_f32 v238, -v238, v241, v240
	v_div_fmas_f32 v238, v238, v239, v241
	v_div_fixup_f32 v244, v238, v237, v236
	v_mov_b32_e32 v236, v109
	v_mov_b32_e32 v237, v105
	v_pk_mul_f32 v[236:237], v[236:237], v[236:237]
	v_mov_b32_e32 v238, v101
	v_mov_b32_e32 v239, v97
	v_pk_mul_f32 v[238:239], v[238:239], v[238:239]
	v_mov_b32_e32 v240, v236
	v_mov_b32_e32 v241, v176
	v_mov_b32_e32 v176, v237
	v_pk_add_f32 v[176:177], v[240:241], v[176:177]
	v_mov_b32_e32 v236, v238
	v_mov_b32_e32 v237, v174
	v_pk_add_f32 v[176:177], v[176:177], v[236:237]
	v_mov_b32_e32 v174, v239
	v_pk_add_f32 v[174:175], v[176:177], v[174:175]
	s_nop 1
	v_mov_b32_dpp v177, v175 quad_perm:[1,0,3,2] row_mask:0xf bank_mask:0xf bound_ctrl:1
	v_mov_b32_dpp v176, v174 quad_perm:[1,0,3,2] row_mask:0xf bank_mask:0xf bound_ctrl:1
	v_pk_add_f32 v[174:175], v[174:175], v[176:177]
	s_nop 1
	v_mov_b32_dpp v177, v175 quad_perm:[2,3,0,1] row_mask:0xf bank_mask:0xf bound_ctrl:1
	v_mov_b32_dpp v176, v174 quad_perm:[2,3,0,1] row_mask:0xf bank_mask:0xf bound_ctrl:1
	v_pk_add_f32 v[174:175], v[174:175], v[176:177]
	s_nop 1
	v_mov_b32_dpp v177, v175 row_ror:4 row_mask:0xf bank_mask:0xf bound_ctrl:1
	v_mov_b32_dpp v176, v174 row_ror:4 row_mask:0xf bank_mask:0xf bound_ctrl:1
	v_pk_add_f32 v[174:175], v[174:175], v[176:177]
	s_nop 1
	v_mov_b32_dpp v177, v175 row_ror:8 row_mask:0xf bank_mask:0xf bound_ctrl:1
	v_mov_b32_dpp v176, v174 row_ror:8 row_mask:0xf bank_mask:0xf bound_ctrl:1
	v_pk_add_f32 v[176:177], v[174:175], v[176:177]
	v_mov_b64_e32 v[174:175], s[0:1]
	s_mov_b32 s0, 0x3c800000
	v_pk_fma_f32 v[176:177], v[176:177], s[0:1], v[174:175] op_sel_hi:[1,0,0]
	s_nop 0
	v_mul_f32_e32 v236, 0x4b800000, v177
	v_cmp_gt_f32_e64 s[8:9], s49, v177
	v_cmp_gt_f32_e32 vcc, s49, v176
	s_nop 0
	v_cndmask_b32_e64 v177, v177, v236, s[8:9]
	v_rsq_f32_e32 v177, v177
	s_nop 0
	v_mul_f32_e32 v236, 0x45800000, v177
	v_cndmask_b32_e64 v177, v177, v236, s[8:9]
	v_mul_f32_e32 v96, v96, v177
	v_mul_f32_e32 v100, v100, v177
	s_waitcnt vmcnt(1)
	v_mul_f32_e32 v100, v232, v100
	v_mul_f32_e32 v100, v243, v100
	v_med3_f32 v100, v100, s57, v194
	s_waitcnt vmcnt(0)
	v_mul_f32_e32 v96, v231, v96
	v_mul_f32_e32 v96, v244, v96
	v_med3_f32 v96, v96, s57, v194
	v_cvt_f16_f32_e32 v96, v96
	v_cvt_f16_f32_e32 v100, v100
	v_mul_f32_e32 v108, v108, v177
	v_mul_f32_e32 v108, v234, v108
	global_store_short v[172:173], v96, off offset:352
	v_mul_f32_e32 v96, 0x4b800000, v176
	v_cndmask_b32_e32 v96, v176, v96, vcc
	v_rsq_f32_e32 v96, v96
	v_mul_f32_e32 v108, v235, v108
	v_med3_f32 v108, v108, s57, v194
	global_store_short v[172:173], v100, off offset:320
	v_mul_f32_e32 v100, 0x45800000, v96
	v_cvt_f16_f32_e32 v108, v108
	v_cndmask_b32_e32 v96, v96, v100, vcc
	v_cvt_f32_f16_e32 v100, v230
	v_mul_f32_e32 v104, v104, v177
	v_mul_f32_e32 v104, v233, v104
	global_store_short v[172:173], v108, off offset:256
	v_mul_f32_e32 v104, v242, v104
	v_mul_f32_e32 v108, 0xbfb8aa3b, v100
	v_med3_f32 v104, v104, s57, v194
	v_exp_f32_e32 v108, v108
	v_cvt_f16_f32_e32 v104, v104
	v_mul_f32_e32 v101, v101, v96
	v_mul_f32_e32 v101, v232, v101
	v_add_f32_e32 v108, 1.0, v108
	global_store_short v[172:173], v104, off offset:288
	v_mul_f32_e32 v104, v109, v96
	v_div_scale_f32 v109, s[8:9], v108, v108, v100
	v_rcp_f32_e32 v172, v109
	v_mul_f32_e32 v104, v234, v104
	v_fma_f32 v173, -v109, v172, 1.0
	v_fmac_f32_e32 v172, v173, v172
	v_div_scale_f32 v173, vcc, v100, v108, v100
	v_mul_f32_e32 v176, v173, v172
	v_fma_f32 v177, -v109, v176, v173
	v_fmac_f32_e32 v176, v177, v172
	v_fma_f32 v109, -v109, v176, v173
	v_div_fmas_f32 v109, v109, v172, v176
	v_div_fixup_f32 v100, v109, v108, v100
	v_mul_f32_e32 v100, v100, v104
	v_med3_f32 v100, v100, s57, v194
	v_cvt_f16_f32_e32 v100, v100
	v_mul_f32_e32 v104, v105, v96
	v_mul_f32_e32 v104, v233, v104
	v_mul_f32_e32 v96, v97, v96
	global_store_short v[170:171], v100, off offset:2560
	v_cvt_f32_f16_e32 v100, v229
	v_mul_f32_e32 v96, v231, v96
	v_mul_f32_e32 v105, 0xbfb8aa3b, v100
	v_exp_f32_e32 v105, v105
	s_nop 0
	v_add_f32_e32 v105, 1.0, v105
	v_div_scale_f32 v108, s[8:9], v105, v105, v100
	v_rcp_f32_e32 v109, v108
	s_nop 0
	v_fma_f32 v172, -v108, v109, 1.0
	v_fmac_f32_e32 v109, v172, v109
	v_div_scale_f32 v172, vcc, v100, v105, v100
	v_mul_f32_e32 v173, v172, v109
	v_fma_f32 v176, -v108, v173, v172
	v_fmac_f32_e32 v173, v176, v109
	v_fma_f32 v108, -v108, v173, v172
	v_div_fmas_f32 v108, v108, v109, v173
	v_div_fixup_f32 v100, v108, v105, v100
	v_mul_f32_e32 v100, v100, v104
	v_med3_f32 v100, v100, s57, v194
	v_cvt_f16_f32_e32 v100, v100
	global_store_short v[170:171], v100, off offset:2592
	v_cvt_f32_f16_e32 v100, v228
	v_mul_f32_e32 v104, 0xbfb8aa3b, v100
	v_exp_f32_e32 v104, v104
	s_nop 0
	v_add_f32_e32 v104, 1.0, v104
	v_div_scale_f32 v105, s[8:9], v104, v104, v100
	v_rcp_f32_e32 v108, v105
	s_nop 0
	v_fma_f32 v109, -v105, v108, 1.0
	v_fmac_f32_e32 v108, v109, v108
	v_div_scale_f32 v109, vcc, v100, v104, v100
	v_mul_f32_e32 v172, v109, v108
	v_fma_f32 v173, -v105, v172, v109
	v_fmac_f32_e32 v172, v173, v108
	v_fma_f32 v105, -v105, v172, v109
	v_div_fmas_f32 v105, v105, v108, v172
	v_div_fixup_f32 v100, v105, v104, v100
	v_mul_f32_e32 v100, v100, v101
	v_med3_f32 v100, v100, s57, v194
	v_cvt_f16_f32_e32 v100, v100
	global_store_short v[170:171], v100, off offset:2624
	v_cvt_f32_f16_e32 v100, v227
	v_mul_f32_e32 v97, 0xbfb8aa3b, v100
	v_exp_f32_e32 v97, v97
	s_nop 0
	v_add_f32_e32 v97, 1.0, v97
	v_div_scale_f32 v101, s[8:9], v97, v97, v100
	v_rcp_f32_e32 v104, v101
	s_nop 0
	v_fma_f32 v105, -v101, v104, 1.0
	v_fmac_f32_e32 v104, v105, v104
	v_div_scale_f32 v105, vcc, v100, v97, v100
	v_mul_f32_e32 v108, v105, v104
	v_fma_f32 v109, -v101, v108, v105
	v_fmac_f32_e32 v108, v109, v104
	v_fma_f32 v101, -v101, v108, v105
	v_div_fmas_f32 v101, v101, v104, v108
	v_cvt_f32_f16_e32 v104, v226
	v_div_fixup_f32 v97, v101, v97, v100
	v_mul_f32_e32 v96, v97, v96
	v_med3_f32 v96, v96, s57, v194
	v_mul_f32_e32 v105, 0xbfb8aa3b, v104
	v_exp_f32_e32 v105, v105
	v_cvt_f16_f32_e32 v96, v96
	v_mov_b32_e32 v97, v106
	v_add_f32_e32 v105, 1.0, v105
	v_div_scale_f32 v108, s[8:9], v105, v105, v104
	v_rcp_f32_e32 v109, v108
	global_store_short v[170:171], v96, off offset:2656
	v_mov_b32_e32 v96, v110
	v_pk_mul_f32 v[100:101], v[96:97], v[96:97]
	v_fma_f32 v170, -v108, v109, 1.0
	v_fmac_f32_e32 v109, v170, v109
	v_div_scale_f32 v170, vcc, v104, v105, v104
	v_mul_f32_e32 v171, v170, v109
	v_fma_f32 v172, -v108, v171, v170
	v_fmac_f32_e32 v171, v172, v109
	v_fma_f32 v108, -v108, v171, v170
	v_div_fmas_f32 v108, v108, v109, v171
	v_div_fixup_f32 v172, v108, v105, v104
	v_cvt_f32_f16_e32 v104, v225
	v_mov_b32_e32 v96, v102
	v_mov_b32_e32 v97, v98
	v_pk_mul_f32 v[96:97], v[96:97], v[96:97]
	v_mul_f32_e32 v105, 0xbfb8aa3b, v104
	v_exp_f32_e32 v105, v105
	s_nop 0
	v_add_f32_e32 v105, 1.0, v105
	v_div_scale_f32 v108, s[8:9], v105, v105, v104
	v_rcp_f32_e32 v109, v108
	s_nop 0
	v_fma_f32 v170, -v108, v109, 1.0
	v_fmac_f32_e32 v109, v170, v109
	v_div_scale_f32 v170, vcc, v104, v105, v104
	v_mul_f32_e32 v171, v170, v109
	v_fma_f32 v173, -v108, v171, v170
	v_fmac_f32_e32 v171, v173, v109
	v_fma_f32 v108, -v108, v171, v170
	v_div_fmas_f32 v108, v108, v109, v171
	v_div_fixup_f32 v173, v108, v105, v104
	v_cvt_f32_f16_e32 v104, v224
	v_mul_f32_e32 v105, 0xbfb8aa3b, v104
	v_exp_f32_e32 v105, v105
	s_nop 0
	v_add_f32_e32 v105, 1.0, v105
	v_div_scale_f32 v108, s[8:9], v105, v105, v104
	v_rcp_f32_e32 v109, v108
	s_nop 0
	v_fma_f32 v170, -v108, v109, 1.0
	v_fmac_f32_e32 v109, v170, v109
	v_div_scale_f32 v170, vcc, v104, v105, v104
	v_mul_f32_e32 v171, v170, v109
	v_fma_f32 v176, -v108, v171, v170
	v_fmac_f32_e32 v171, v176, v109
	v_fma_f32 v108, -v108, v171, v170
	v_div_fmas_f32 v108, v108, v109, v171
	v_div_fixup_f32 v176, v108, v105, v104
	v_cvt_f32_f16_e32 v104, v223
	v_mul_f32_e32 v105, 0xbfb8aa3b, v104
	v_exp_f32_e32 v105, v105
	s_nop 0
	v_add_f32_e32 v105, 1.0, v105
	v_div_scale_f32 v108, s[8:9], v105, v105, v104
	v_rcp_f32_e32 v109, v108
	s_nop 0
	v_fma_f32 v170, -v108, v109, 1.0
	v_fmac_f32_e32 v109, v170, v109
	v_div_scale_f32 v170, vcc, v104, v105, v104
	v_mul_f32_e32 v171, v170, v109
	v_fma_f32 v177, -v108, v171, v170
	v_fmac_f32_e32 v171, v177, v109
	v_fma_f32 v108, -v108, v171, v170
	v_div_fmas_f32 v108, v108, v109, v171
	v_div_fixup_f32 v177, v108, v105, v104
	v_mov_b32_e32 v104, v111
	v_mov_b32_e32 v105, v107
	v_pk_mul_f32 v[104:105], v[104:105], v[104:105]
	v_mov_b32_e32 v108, v103
	v_mov_b32_e32 v109, v99
	v_pk_mul_f32 v[108:109], v[108:109], v[108:109]
	v_mov_b32_e32 v170, v104
	v_mov_b32_e32 v171, v100
	v_mov_b32_e32 v100, v105
	v_pk_add_f32 v[100:101], v[170:171], v[100:101]
	v_mov_b32_e32 v104, v108
	v_mov_b32_e32 v105, v96
	v_pk_add_f32 v[100:101], v[100:101], v[104:105]
	v_mov_b32_e32 v96, v109
	v_pk_add_f32 v[96:97], v[100:101], v[96:97]
	s_nop 1
	v_mov_b32_dpp v101, v97 quad_perm:[1,0,3,2] row_mask:0xf bank_mask:0xf bound_ctrl:1
	v_mov_b32_dpp v100, v96 quad_perm:[1,0,3,2] row_mask:0xf bank_mask:0xf bound_ctrl:1
	v_pk_add_f32 v[96:97], v[96:97], v[100:101]
	s_nop 1
	v_mov_b32_dpp v101, v97 quad_perm:[2,3,0,1] row_mask:0xf bank_mask:0xf bound_ctrl:1
	v_mov_b32_dpp v100, v96 quad_perm:[2,3,0,1] row_mask:0xf bank_mask:0xf bound_ctrl:1
	v_pk_add_f32 v[96:97], v[96:97], v[100:101]
	s_nop 1
	v_mov_b32_dpp v101, v97 row_ror:4 row_mask:0xf bank_mask:0xf bound_ctrl:1
	v_mov_b32_dpp v100, v96 row_ror:4 row_mask:0xf bank_mask:0xf bound_ctrl:1
	v_pk_add_f32 v[96:97], v[96:97], v[100:101]
	s_nop 1
	v_mov_b32_dpp v101, v97 row_ror:8 row_mask:0xf bank_mask:0xf bound_ctrl:1
	v_mov_b32_dpp v100, v96 row_ror:8 row_mask:0xf bank_mask:0xf bound_ctrl:1
	v_pk_add_f32 v[96:97], v[96:97], v[100:101]
	s_nop 0
	v_pk_fma_f32 v[96:97], v[96:97], s[0:1], v[174:175] op_sel_hi:[1,0,0]
	s_nop 0
	v_mul_f32_e32 v100, 0x4b800000, v97
	v_cmp_gt_f32_e64 s[8:9], s49, v97
	v_cmp_gt_f32_e32 vcc, s49, v96
	s_nop 0
	v_cndmask_b32_e64 v97, v97, v100, s[8:9]
	v_rsq_f32_e32 v97, v97
	s_nop 0
	v_mul_f32_e32 v100, 0x45800000, v97
	v_cndmask_b32_e64 v97, v97, v100, s[8:9]
	v_mul_f32_e32 v100, v110, v97
	v_mul_f32_e32 v100, v234, v100
	v_mul_f32_e32 v100, v172, v100
	v_med3_f32 v100, v100, s57, v194
	v_cvt_f16_f32_e32 v100, v100
	global_store_short v[168:169], v100, off offset:768
	v_mul_f32_e32 v100, v106, v97
	v_mul_f32_e32 v100, v233, v100
	v_mul_f32_e32 v100, v173, v100
	v_med3_f32 v100, v100, s57, v194
	v_cvt_f16_f32_e32 v100, v100
	global_store_short v[168:169], v100, off offset:800
	v_mul_f32_e32 v100, v102, v97
	v_mul_f32_e32 v97, v98, v97
	v_mul_f32_e32 v97, v231, v97
	v_mul_f32_e32 v97, v177, v97
	v_med3_f32 v97, v97, s57, v194
	v_cvt_f16_f32_e32 v97, v97
	v_mul_f32_e32 v100, v232, v100
	v_mul_f32_e32 v100, v176, v100
	v_med3_f32 v100, v100, s57, v194
	global_store_short v[168:169], v97, off offset:864
	v_mul_f32_e32 v97, 0x4b800000, v96
	v_cndmask_b32_e32 v96, v96, v97, vcc
	v_rsq_f32_e32 v96, v96
	v_cvt_f16_f32_e32 v100, v100
	v_mul_f32_e32 v97, 0x45800000, v96
	v_cndmask_b32_e32 v96, v96, v97, vcc
	v_cvt_f32_f16_e32 v97, v181
	global_store_short v[168:169], v100, off offset:832
	v_mul_f32_e32 v98, v111, v96
	v_mul_f32_e32 v98, v234, v98
	v_mul_f32_e32 v100, 0xbfb8aa3b, v97
	v_exp_f32_e32 v100, v100
	s_nop 0
	v_add_f32_e32 v100, 1.0, v100
	v_div_scale_f32 v101, s[8:9], v100, v100, v97
	v_rcp_f32_e32 v102, v101
	s_nop 0
	v_fma_f32 v104, -v101, v102, 1.0
	v_fmac_f32_e32 v102, v104, v102
	v_div_scale_f32 v104, vcc, v97, v100, v97
	v_mul_f32_e32 v105, v104, v102
	v_fma_f32 v106, -v101, v105, v104
	v_fmac_f32_e32 v105, v106, v102
	v_fma_f32 v101, -v101, v105, v104
	v_div_fmas_f32 v101, v101, v102, v105
	v_div_fixup_f32 v97, v101, v100, v97
	v_mul_f32_e32 v97, v97, v98
	v_med3_f32 v97, v97, s57, v194
	v_cvt_f16_f32_e32 v97, v97
	v_mul_f32_e32 v98, v107, v96
	v_mul_f32_e32 v98, v233, v98
	global_store_short v[166:167], v97, off offset:3072
	v_cvt_f32_f16_e32 v97, v180
	v_mul_f32_e32 v100, 0xbfb8aa3b, v97
	v_exp_f32_e32 v100, v100
	s_nop 0
	v_add_f32_e32 v100, 1.0, v100
	v_div_scale_f32 v101, s[8:9], v100, v100, v97
	v_rcp_f32_e32 v102, v101
	s_nop 0
	v_fma_f32 v104, -v101, v102, 1.0
	v_fmac_f32_e32 v102, v104, v102
	v_div_scale_f32 v104, vcc, v97, v100, v97
	v_mul_f32_e32 v105, v104, v102
	v_fma_f32 v106, -v101, v105, v104
	v_fmac_f32_e32 v105, v106, v102
	v_fma_f32 v101, -v101, v105, v104
	v_div_fmas_f32 v101, v101, v102, v105
	v_div_fixup_f32 v97, v101, v100, v97
	v_mul_f32_e32 v97, v97, v98
	v_med3_f32 v97, v97, s57, v194
	v_cvt_f16_f32_e32 v97, v97
	v_mul_f32_e32 v98, v103, v96
	v_mul_f32_e32 v98, v232, v98
	v_mul_f32_e32 v96, v99, v96
	global_store_short v[166:167], v97, off offset:3104
	v_cvt_f32_f16_e32 v97, v179
	v_mul_f32_e32 v96, v231, v96
	v_mul_f32_e32 v100, 0xbfb8aa3b, v97
	v_exp_f32_e32 v100, v100
	s_nop 0
	v_add_f32_e32 v100, 1.0, v100
	v_div_scale_f32 v101, s[8:9], v100, v100, v97
	v_rcp_f32_e32 v102, v101
	s_nop 0
	v_fma_f32 v103, -v101, v102, 1.0
	v_fmac_f32_e32 v102, v103, v102
	v_div_scale_f32 v103, vcc, v97, v100, v97
	v_mul_f32_e32 v104, v103, v102
	v_fma_f32 v105, -v101, v104, v103
	v_fmac_f32_e32 v104, v105, v102
	v_fma_f32 v101, -v101, v104, v103
	v_div_fmas_f32 v101, v101, v102, v104
	v_div_fixup_f32 v97, v101, v100, v97
	v_mul_f32_e32 v97, v97, v98
	v_med3_f32 v97, v97, s57, v194
	v_cvt_f16_f32_e32 v97, v97
	global_store_short v[166:167], v97, off offset:3136
	v_cvt_f32_f16_e32 v97, v178
	v_mul_f32_e32 v98, 0xbfb8aa3b, v97
	v_exp_f32_e32 v98, v98
	s_nop 0
	v_add_f32_e32 v98, 1.0, v98
	v_div_scale_f32 v99, s[8:9], v98, v98, v97
	v_rcp_f32_e32 v100, v99
	s_nop 0
	v_fma_f32 v101, -v99, v100, 1.0
	v_fmac_f32_e32 v100, v101, v100
	v_div_scale_f32 v101, vcc, v97, v98, v97
	v_mul_f32_e32 v102, v101, v100
	v_fma_f32 v103, -v99, v102, v101
	v_fmac_f32_e32 v102, v103, v100
	v_fma_f32 v99, -v99, v102, v101
	v_div_fmas_f32 v99, v99, v100, v102
	v_div_fixup_f32 v97, v99, v98, v97
	v_mul_f32_e32 v96, v97, v96
	v_med3_f32 v96, v96, s57, v194
	v_cvt_f16_f32_e32 v96, v96
	s_andn2_b64 vcc, exec, s[10:11]
	global_store_short v[166:167], v96, off offset:3168
	ds_read_b128 v[96:99], v116 offset:55296
	ds_read_b128 v[240:243], v117 offset:36864
	ds_read_b128 v[244:247], v117 offset:39168
	ds_read_b128 v[252:255], v117 offset:41472
	s_waitcnt lgkmcnt(2)
	v_mul_f32_e64 v82, v82, v112
	v_mul_f32_e64 v83, v83, v112
	v_pk_mul_f32 v[80:81], v[80:81], v[112:113] op_sel_hi:[1,0]
	v_pk_mul_f32 v[86:87], v[86:87], v[112:113] op_sel_hi:[1,0]
	v_mul_f32_e64 v84, v84, v112
	v_mul_f32_e64 v85, v85, v112
	v_pk_mul_f32 v[90:91], v[90:91], v[112:113] op_sel_hi:[1,0]
	v_pk_mul_f32 v[88:89], v[88:89], v[112:113] op_sel_hi:[1,0]
	v_pk_mul_f32 v[94:95], v[94:95], v[112:113] op_sel_hi:[1,0]
	v_pk_mul_f32 v[92:93], v[92:93], v[112:113] op_sel_hi:[1,0]
	s_nop 1
	v_mfma_f32_16x16x32_f16 v[80:83], v[96:99], v[240:243], v[80:83]
	ds_read_b128 v[240:243], v117 offset:43776
	ds_read_b128 v[100:103], v116 offset:55360
	s_waitcnt lgkmcnt(3)
	v_mfma_f32_16x16x32_f16 v[84:87], v[96:99], v[244:247], v[84:87]
	ds_read_b128 v[244:247], v117 offset:36928
	s_waitcnt lgkmcnt(3)
	v_mfma_f32_16x16x32_f16 v[88:91], v[96:99], v[252:255], v[88:91]
	ds_read_b128 v[252:255], v117 offset:39232
	s_waitcnt lgkmcnt(3)
	v_mfma_f32_16x16x32_f16 v[92:95], v[96:99], v[240:243], v[92:95]
	ds_read_b128 v[240:243], v117 offset:41536
	s_waitcnt lgkmcnt(2)
	v_mfma_f32_16x16x32_f16 v[80:83], v[100:103], v[244:247], v[80:83]
	ds_read_b128 v[244:247], v117 offset:43840
	s_waitcnt lgkmcnt(2)
	v_mfma_f32_16x16x32_f16 v[84:87], v[100:103], v[252:255], v[84:87]
	s_waitcnt lgkmcnt(1)
	v_mfma_f32_16x16x32_f16 v[88:91], v[100:103], v[240:243], v[88:91]
	s_waitcnt lgkmcnt(0)
	s_barrier
	v_mfma_f32_16x16x32_f16 v[92:95], v[100:103], v[244:247], v[92:95]
	v_med3_f32 v96, v80, s57, v194
	v_cvt_f16_f32_e32 v96, v96
	ds_write_b16 v215, v96 offset:46080
	v_med3_f32 v96, v81, s57, v194
	v_cvt_f16_f32_e32 v96, v96
	ds_write_b16 v215, v96 offset:46224
	v_med3_f32 v96, v82, s57, v194
	v_cvt_f16_f32_e32 v96, v96
	ds_write_b16 v215, v96 offset:46368
	v_med3_f32 v96, v83, s57, v194
	v_cvt_f16_f32_e32 v96, v96
	ds_write_b16 v215, v96 offset:46512
	v_med3_f32 v96, v84, s57, v194
	v_cvt_f16_f32_e32 v96, v96
	ds_write_b16 v215, v96 offset:46112
	v_med3_f32 v96, v85, s57, v194
	v_cvt_f16_f32_e32 v96, v96
	ds_write_b16 v216, v96 offset:46224
	v_med3_f32 v96, v86, s57, v194
	v_cvt_f16_f32_e32 v96, v96
	ds_write_b16 v216, v96 offset:46368
	v_med3_f32 v96, v87, s57, v194
	v_cvt_f16_f32_e32 v96, v96
	ds_write_b16 v216, v96 offset:46512
	v_med3_f32 v96, v88, s57, v194
	v_cvt_f16_f32_e32 v96, v96
	ds_write_b16 v215, v96 offset:46144
	v_med3_f32 v96, v89, s57, v194
	v_cvt_f16_f32_e32 v96, v96
	ds_write_b16 v217, v96 offset:46224
	v_med3_f32 v96, v90, s57, v194
	v_cvt_f16_f32_e32 v96, v96
	ds_write_b16 v217, v96 offset:46368
	v_med3_f32 v96, v91, s57, v194
	v_cvt_f16_f32_e32 v96, v96
	ds_write_b16 v217, v96 offset:46512
	v_med3_f32 v96, v92, s57, v194
	v_cvt_f16_f32_e32 v96, v96
	ds_write_b16 v215, v96 offset:46176
	v_med3_f32 v96, v93, s57, v194
	v_cvt_f16_f32_e32 v96, v96
	ds_write_b16 v218, v96 offset:46224
	v_med3_f32 v96, v94, s57, v194
	v_cvt_f16_f32_e32 v96, v96
	ds_write_b16 v218, v96 offset:46368
	v_med3_f32 v96, v95, s57, v194
	v_cvt_f16_f32_e32 v96, v96
	ds_write_b16 v218, v96 offset:46512
	ds_write_b128 v220, v[16:19]
	ds_write_b128 v211, v[20:23]
	ds_write_b128 v221, v[24:27]
	ds_write_b128 v212, v[28:31]
	ds_write_b128 v222, v[32:35]
	ds_write_b128 v213, v[36:39]
	s_waitcnt lgkmcnt(0)

.LBB0_527:
	s_mov_b64 s[8:9], 0x65100
	v_lshl_add_u64 v[178:179], v[108:109], 0, s[8:9]
	s_mov_b64 s[8:9], 0x65120
	v_lshl_add_u64 v[176:177], v[108:109], 0, s[8:9]
	s_mov_b64 s[8:9], 0x65140
	v_lshl_add_u64 v[174:175], v[108:109], 0, s[8:9]
	s_mov_b64 s[8:9], 0x65160
	v_lshl_add_u64 v[172:173], v[108:109], 0, s[8:9]
	s_mov_b64 s[8:9], 0x66a00
	v_lshl_add_u64 v[168:169], v[108:109], 0, s[8:9]
	s_mov_b64 s[8:9], 0x66a20
	v_lshl_add_u64 v[166:167], v[108:109], 0, s[8:9]
	s_mov_b64 s[8:9], 0x66a40
	v_lshl_add_u64 v[164:165], v[108:109], 0, s[8:9]
	s_mov_b64 s[8:9], 0x66a60
	v_lshl_add_u64 v[162:163], v[108:109], 0, s[8:9]
	s_mov_b64 s[8:9], 0x68300
	v_lshl_add_u64 v[160:161], v[108:109], 0, s[8:9]
	s_mov_b64 s[8:9], 0x68320
	v_lshl_add_u64 v[158:159], v[108:109], 0, s[8:9]
	s_mov_b64 s[8:9], 0x68340
	v_lshl_add_u64 v[156:157], v[108:109], 0, s[8:9]
	s_mov_b64 s[8:9], 0x68360
	v_lshl_add_u64 v[154:155], v[108:109], 0, s[8:9]
	s_mov_b64 s[8:9], 0x69c00
	v_lshl_add_u64 v[152:153], v[108:109], 0, s[8:9]
	s_mov_b64 s[8:9], 0x69c20
	v_lshl_add_u64 v[150:151], v[108:109], 0, s[8:9]
	s_mov_b64 s[8:9], 0x69c40
	v_lshl_add_u64 v[148:149], v[108:109], 0, s[8:9]
	s_mov_b64 s[8:9], 0x69c60
	v_lshl_add_u64 v[146:147], v[108:109], 0, s[8:9]
	s_waitcnt vmcnt(15)
	v_cvt_f32_f16_e32 v239, v238
	s_mov_b32 s0, 0x358637bd
	global_load_dword v238, v[118:119], off
	ds_read_b128 v[240:243], v116 offset:27648
	ds_read_b128 v[244:247], v117 offset:46080
	ds_read_b128 v[252:255], v117 offset:48384
	s_waitcnt lgkmcnt(1)
	v_mfma_f32_16x16x32_f16 v[108:111], v[240:243], v[244:247], 0
	ds_read_b128 v[244:247], v117 offset:50688
	s_waitcnt lgkmcnt(1)
	v_mfma_f32_16x16x32_f16 v[104:107], v[240:243], v[252:255], 0
	ds_read_b128 v[252:255], v117 offset:52992
	s_waitcnt lgkmcnt(1)
	v_mfma_f32_16x16x32_f16 v[100:103], v[240:243], v[244:247], 0
	s_waitcnt lgkmcnt(0)
	v_mfma_f32_16x16x32_f16 v[96:99], v[240:243], v[252:255], 0
	ds_read_b128 v[240:243], v116 offset:27712
	ds_read_b128 v[244:247], v117 offset:46144
	ds_read_b128 v[252:255], v117 offset:48448
	s_waitcnt lgkmcnt(1)
	v_mfma_f32_16x16x32_f16 v[108:111], v[240:243], v[244:247], v[108:111]
	ds_read_b128 v[244:247], v117 offset:50752
	s_waitcnt lgkmcnt(1)
	v_mfma_f32_16x16x32_f16 v[104:107], v[240:243], v[252:255], v[104:107]
	ds_read_b128 v[252:255], v117 offset:53056
	s_waitcnt lgkmcnt(1)
	v_mfma_f32_16x16x32_f16 v[100:103], v[240:243], v[244:247], v[100:103]
	s_waitcnt lgkmcnt(0)
	v_mfma_f32_16x16x32_f16 v[96:99], v[240:243], v[252:255], v[96:99]
	ds_read_b128 v[240:243], v116 offset:18432
	ds_read_b128 v[244:247], v117 offset:55296
	ds_read_b128 v[252:255], v117 offset:57600
	s_waitcnt lgkmcnt(1)
	v_mfma_f32_16x16x32_f16 v[108:111], v[240:243], v[244:247], v[108:111]
	ds_read_b128 v[244:247], v117 offset:59904
	s_waitcnt lgkmcnt(1)
	v_mfma_f32_16x16x32_f16 v[104:107], v[240:243], v[252:255], v[104:107]
	ds_read_b128 v[252:255], v117 offset:62208
	s_waitcnt lgkmcnt(1)
	v_mfma_f32_16x16x32_f16 v[100:103], v[240:243], v[244:247], v[100:103]
	s_waitcnt lgkmcnt(0)
	v_mfma_f32_16x16x32_f16 v[96:99], v[240:243], v[252:255], v[96:99]
	ds_read_b128 v[240:243], v116 offset:18496
	ds_read_b128 v[244:247], v117 offset:55360
	ds_read_b128 v[252:255], v117 offset:57664
	s_waitcnt lgkmcnt(1)
	v_mfma_f32_16x16x32_f16 v[108:111], v[240:243], v[244:247], v[108:111]
	ds_read_b128 v[244:247], v117 offset:59968
	s_waitcnt lgkmcnt(1)
	v_mfma_f32_16x16x32_f16 v[104:107], v[240:243], v[252:255], v[104:107]
	s_nop 7
	v_mov_b32_e32 v170, v108
	v_mov_b32_e32 v171, v104
	ds_read_b128 v[252:255], v117 offset:62272
	s_waitcnt lgkmcnt(1)
	v_mfma_f32_16x16x32_f16 v[100:103], v[240:243], v[244:247], v[100:103]
	s_nop 7
	v_mul_f32_e64 v180, v170, v170
	v_mul_f32_e64 v181, v171, v171
	s_waitcnt lgkmcnt(0)
	v_mfma_f32_16x16x32_f16 v[96:99], v[240:243], v[252:255], v[96:99]
	v_mul_f32_e32 v240, 0xbfb8aa3b, v239
	v_exp_f32_e32 v240, v240
	v_mov_b32_e32 v170, v100
	s_nop 4
	v_mov_b32_e32 v171, v96
	v_pk_mul_f32 v[170:171], v[170:171], v[170:171]
	v_add_f32_e32 v240, 1.0, v240
	v_div_scale_f32 v241, s[8:9], v240, v240, v239
	v_rcp_f32_e32 v242, v241
	s_nop 0
	v_fma_f32 v243, -v241, v242, 1.0
	v_fmac_f32_e32 v242, v243, v242
	v_div_scale_f32 v243, vcc, v239, v240, v239
	v_mul_f32_e32 v244, v243, v242
	v_fma_f32 v245, -v241, v244, v243
	v_fmac_f32_e32 v244, v245, v242
	v_fma_f32 v241, -v241, v244, v243
	v_div_fmas_f32 v241, v241, v242, v244
	v_div_fixup_f32 v239, v241, v240, v239
	s_waitcnt vmcnt(15)
	v_cvt_f32_f16_e32 v240, v237
	global_load_dword v237, v[118:119], off offset:64
	v_mul_f32_e32 v241, 0xbfb8aa3b, v240
	v_exp_f32_e32 v241, v241
	s_nop 0
	v_add_f32_e32 v241, 1.0, v241
	v_div_scale_f32 v242, s[8:9], v241, v241, v240
	v_rcp_f32_e32 v243, v242
	s_nop 0
	v_fma_f32 v244, -v242, v243, 1.0
	v_fmac_f32_e32 v243, v244, v243
	v_div_scale_f32 v244, vcc, v240, v241, v240
	v_mul_f32_e32 v245, v244, v243
	v_fma_f32 v246, -v242, v245, v244
	v_fmac_f32_e32 v245, v246, v243
	v_fma_f32 v242, -v242, v245, v244
	v_div_fmas_f32 v242, v242, v243, v245
	v_div_fixup_f32 v246, v242, v241, v240
	s_waitcnt vmcnt(15)
	v_cvt_f32_f16_e32 v240, v236
	global_load_dword v236, v[118:119], off offset:128
	v_mul_f32_e32 v241, 0xbfb8aa3b, v240
	v_exp_f32_e32 v241, v241
	s_nop 0
	v_add_f32_e32 v241, 1.0, v241
	v_div_scale_f32 v242, s[8:9], v241, v241, v240
	v_rcp_f32_e32 v243, v242
	s_nop 0
	v_fma_f32 v244, -v242, v243, 1.0
	v_fmac_f32_e32 v243, v244, v243
	v_div_scale_f32 v244, vcc, v240, v241, v240
	v_mul_f32_e32 v245, v244, v243
	v_fma_f32 v247, -v242, v245, v244
	v_fmac_f32_e32 v245, v247, v243
	v_fma_f32 v242, -v242, v245, v244
	v_div_fmas_f32 v242, v242, v243, v245
	v_div_fixup_f32 v247, v242, v241, v240
	s_waitcnt vmcnt(15)
	v_cvt_f32_f16_e32 v240, v235
	global_load_dword v235, v[118:119], off offset:192
	v_mul_f32_e32 v241, 0xbfb8aa3b, v240
	v_exp_f32_e32 v241, v241
	s_nop 0
	v_add_f32_e32 v241, 1.0, v241
	v_div_scale_f32 v242, s[8:9], v241, v241, v240
	v_rcp_f32_e32 v243, v242
	s_nop 0
	v_fma_f32 v244, -v242, v243, 1.0
	v_fmac_f32_e32 v243, v244, v243
	v_div_scale_f32 v244, vcc, v240, v241, v240
	v_mul_f32_e32 v245, v244, v243
	v_fma_f32 v248, -v242, v245, v244
	v_fmac_f32_e32 v245, v248, v243
	v_fma_f32 v242, -v242, v245, v244
	v_div_fmas_f32 v242, v242, v243, v245
	v_div_fixup_f32 v248, v242, v241, v240
	v_mov_b32_e32 v240, v109
	v_mov_b32_e32 v241, v105
	v_pk_mul_f32 v[240:241], v[240:241], v[240:241]
	v_mov_b32_e32 v242, v101
	v_mov_b32_e32 v243, v97
	v_pk_mul_f32 v[242:243], v[242:243], v[242:243]
	v_mov_b32_e32 v244, v240
	v_mov_b32_e32 v245, v180
	v_mov_b32_e32 v180, v241
	v_pk_add_f32 v[180:181], v[244:245], v[180:181]
	v_mov_b32_e32 v240, v242
	v_mov_b32_e32 v241, v170
	v_pk_add_f32 v[180:181], v[180:181], v[240:241]
	v_mov_b32_e32 v170, v243
	v_pk_add_f32 v[170:171], v[180:181], v[170:171]
	s_nop 1
	v_mov_b32_dpp v181, v171 quad_perm:[1,0,3,2] row_mask:0xf bank_mask:0xf bound_ctrl:1
	v_mov_b32_dpp v180, v170 quad_perm:[1,0,3,2] row_mask:0xf bank_mask:0xf bound_ctrl:1
	v_pk_add_f32 v[170:171], v[170:171], v[180:181]
	s_nop 1
	v_mov_b32_dpp v181, v171 quad_perm:[2,3,0,1] row_mask:0xf bank_mask:0xf bound_ctrl:1
	v_mov_b32_dpp v180, v170 quad_perm:[2,3,0,1] row_mask:0xf bank_mask:0xf bound_ctrl:1
	v_pk_add_f32 v[170:171], v[170:171], v[180:181]
	s_nop 1
	v_mov_b32_dpp v181, v171 row_ror:4 row_mask:0xf bank_mask:0xf bound_ctrl:1
	v_mov_b32_dpp v180, v170 row_ror:4 row_mask:0xf bank_mask:0xf bound_ctrl:1
	v_pk_add_f32 v[170:171], v[170:171], v[180:181]
	s_nop 1
	v_mov_b32_dpp v181, v171 row_ror:8 row_mask:0xf bank_mask:0xf bound_ctrl:1
	v_mov_b32_dpp v180, v170 row_ror:8 row_mask:0xf bank_mask:0xf bound_ctrl:1
	v_pk_add_f32 v[180:181], v[170:171], v[180:181]
	v_mov_b64_e32 v[170:171], s[0:1]
	s_mov_b32 s0, 0x3c800000
	v_pk_fma_f32 v[180:181], v[180:181], s[0:1], v[170:171] op_sel_hi:[1,0,0]
	s_nop 0
	v_mul_f32_e32 v240, 0x4b800000, v181
	v_cmp_gt_f32_e64 s[8:9], s49, v181
	v_cmp_gt_f32_e32 vcc, s49, v180
	s_nop 0
	v_cndmask_b32_e64 v181, v181, v240, s[8:9]
	v_rsq_f32_e32 v181, v181
	s_nop 0
	v_mul_f32_e32 v240, 0x45800000, v181
	v_cndmask_b32_e64 v181, v181, v240, s[8:9]
	v_mul_f32_e32 v96, v96, v181
	v_mul_f32_e32 v100, v100, v181
	s_waitcnt vmcnt(1)
	v_mul_f32_e32 v100, v236, v100
	v_mul_f32_e32 v100, v247, v100
	v_med3_f32 v100, v100, s57, v194
	s_waitcnt vmcnt(0)
	v_mul_f32_e32 v96, v235, v96
	v_mul_f32_e32 v96, v248, v96
	v_med3_f32 v96, v96, s57, v194
	v_cvt_f16_f32_e32 v96, v96
	v_cvt_f16_f32_e32 v100, v100
	v_mul_f32_e32 v108, v108, v181
	v_mul_f32_e32 v108, v238, v108
	global_store_short v[172:173], v96, off
	v_mul_f32_e32 v96, 0x4b800000, v180
	v_cndmask_b32_e32 v96, v180, v96, vcc
	v_rsq_f32_e32 v96, v96
	v_mul_f32_e32 v108, v239, v108
	v_med3_f32 v108, v108, s57, v194
	global_store_short v[174:175], v100, off
	v_mul_f32_e32 v100, 0x45800000, v96
	v_cvt_f16_f32_e32 v108, v108
	v_cndmask_b32_e32 v96, v96, v100, vcc
	v_cvt_f32_f16_e32 v100, v234
	v_mul_f32_e32 v104, v104, v181
	v_mul_f32_e32 v104, v237, v104
	global_store_short v[178:179], v108, off
	v_mul_f32_e32 v104, v246, v104
	v_mul_f32_e32 v108, 0xbfb8aa3b, v100
	v_med3_f32 v104, v104, s57, v194
	v_exp_f32_e32 v108, v108
	v_cvt_f16_f32_e32 v104, v104
	v_mul_f32_e32 v101, v101, v96
	v_mul_f32_e32 v101, v236, v101
	v_add_f32_e32 v108, 1.0, v108
	global_store_short v[176:177], v104, off
	v_mul_f32_e32 v104, v109, v96
	v_div_scale_f32 v109, s[8:9], v108, v108, v100
	v_rcp_f32_e32 v172, v109
	v_mul_f32_e32 v104, v238, v104
	v_fma_f32 v173, -v109, v172, 1.0
	v_fmac_f32_e32 v172, v173, v172
	v_div_scale_f32 v173, vcc, v100, v108, v100
	v_mul_f32_e32 v174, v173, v172
	v_fma_f32 v175, -v109, v174, v173
	v_fmac_f32_e32 v174, v175, v172
	v_fma_f32 v109, -v109, v174, v173
	v_div_fmas_f32 v109, v109, v172, v174
	v_div_fixup_f32 v100, v109, v108, v100
	v_mul_f32_e32 v100, v100, v104
	v_med3_f32 v100, v100, s57, v194
	v_cvt_f16_f32_e32 v100, v100
	v_mul_f32_e32 v104, v105, v96
	v_mul_f32_e32 v104, v237, v104
	v_mul_f32_e32 v96, v97, v96
	global_store_short v[168:169], v100, off
	v_cvt_f32_f16_e32 v100, v233
	v_mul_f32_e32 v96, v235, v96
	v_mul_f32_e32 v105, 0xbfb8aa3b, v100
	v_exp_f32_e32 v105, v105
	s_nop 0
	v_add_f32_e32 v105, 1.0, v105
	v_div_scale_f32 v108, s[8:9], v105, v105, v100
	v_rcp_f32_e32 v109, v108
	s_nop 0
	v_fma_f32 v168, -v108, v109, 1.0
	v_fmac_f32_e32 v109, v168, v109
	v_div_scale_f32 v168, vcc, v100, v105, v100
	v_mul_f32_e32 v169, v168, v109
	v_fma_f32 v172, -v108, v169, v168
	v_fmac_f32_e32 v169, v172, v109
	v_fma_f32 v108, -v108, v169, v168
	v_div_fmas_f32 v108, v108, v109, v169
	v_div_fixup_f32 v100, v108, v105, v100
	v_mul_f32_e32 v100, v100, v104
	v_med3_f32 v100, v100, s57, v194
	v_cvt_f16_f32_e32 v100, v100
	global_store_short v[166:167], v100, off
	v_cvt_f32_f16_e32 v100, v232
	v_mul_f32_e32 v104, 0xbfb8aa3b, v100
	v_exp_f32_e32 v104, v104
	s_nop 0
	v_add_f32_e32 v104, 1.0, v104
	v_div_scale_f32 v105, s[8:9], v104, v104, v100
	v_rcp_f32_e32 v108, v105
	s_nop 0
	v_fma_f32 v109, -v105, v108, 1.0
	v_fmac_f32_e32 v108, v109, v108
	v_div_scale_f32 v109, vcc, v100, v104, v100
	v_mul_f32_e32 v166, v109, v108
	v_fma_f32 v167, -v105, v166, v109
	v_fmac_f32_e32 v166, v167, v108
	v_fma_f32 v105, -v105, v166, v109
	v_div_fmas_f32 v105, v105, v108, v166
	v_div_fixup_f32 v100, v105, v104, v100
	v_mul_f32_e32 v100, v100, v101
	v_med3_f32 v100, v100, s57, v194
	v_cvt_f16_f32_e32 v100, v100
	global_store_short v[164:165], v100, off
	v_cvt_f32_f16_e32 v100, v231
	v_mul_f32_e32 v97, 0xbfb8aa3b, v100
	v_exp_f32_e32 v97, v97
	s_nop 0
	v_add_f32_e32 v97, 1.0, v97
	v_div_scale_f32 v101, s[8:9], v97, v97, v100
	v_rcp_f32_e32 v104, v101
	s_nop 0
	v_fma_f32 v105, -v101, v104, 1.0
	v_fmac_f32_e32 v104, v105, v104
	v_div_scale_f32 v105, vcc, v100, v97, v100
	v_mul_f32_e32 v108, v105, v104
	v_fma_f32 v109, -v101, v108, v105
	v_fmac_f32_e32 v108, v109, v104
	v_fma_f32 v101, -v101, v108, v105
	v_div_fmas_f32 v101, v101, v104, v108
	v_cvt_f32_f16_e32 v104, v230
	v_div_fixup_f32 v97, v101, v97, v100
	v_mul_f32_e32 v96, v97, v96
	v_med3_f32 v96, v96, s57, v194
	v_mul_f32_e32 v105, 0xbfb8aa3b, v104
	v_exp_f32_e32 v105, v105
	v_cvt_f16_f32_e32 v96, v96
	v_mov_b32_e32 v97, v106
	v_add_f32_e32 v105, 1.0, v105
	v_div_scale_f32 v108, s[8:9], v105, v105, v104
	v_rcp_f32_e32 v109, v108
	global_store_short v[162:163], v96, off
	v_mov_b32_e32 v96, v110
	v_pk_mul_f32 v[100:101], v[96:97], v[96:97]
	v_fma_f32 v162, -v108, v109, 1.0
	v_fmac_f32_e32 v109, v162, v109
	v_div_scale_f32 v162, vcc, v104, v105, v104
	v_mul_f32_e32 v163, v162, v109
	v_fma_f32 v164, -v108, v163, v162
	v_fmac_f32_e32 v163, v164, v109
	v_fma_f32 v108, -v108, v163, v162
	v_div_fmas_f32 v108, v108, v109, v163
	v_div_fixup_f32 v164, v108, v105, v104
	v_cvt_f32_f16_e32 v104, v229
	v_mov_b32_e32 v96, v102
	v_mov_b32_e32 v97, v98
	v_pk_mul_f32 v[96:97], v[96:97], v[96:97]
	v_mul_f32_e32 v105, 0xbfb8aa3b, v104
	v_exp_f32_e32 v105, v105
	s_nop 0
	v_add_f32_e32 v105, 1.0, v105
	v_div_scale_f32 v108, s[8:9], v105, v105, v104
	v_rcp_f32_e32 v109, v108
	s_nop 0
	v_fma_f32 v162, -v108, v109, 1.0
	v_fmac_f32_e32 v109, v162, v109
	v_div_scale_f32 v162, vcc, v104, v105, v104
	v_mul_f32_e32 v163, v162, v109
	v_fma_f32 v165, -v108, v163, v162
	v_fmac_f32_e32 v163, v165, v109
	v_fma_f32 v108, -v108, v163, v162
	v_div_fmas_f32 v108, v108, v109, v163
	v_div_fixup_f32 v165, v108, v105, v104
	v_cvt_f32_f16_e32 v104, v228
	v_mul_f32_e32 v105, 0xbfb8aa3b, v104
	v_exp_f32_e32 v105, v105
	s_nop 0
	v_add_f32_e32 v105, 1.0, v105
	v_div_scale_f32 v108, s[8:9], v105, v105, v104
	v_rcp_f32_e32 v109, v108
	s_nop 0
	v_fma_f32 v162, -v108, v109, 1.0
	v_fmac_f32_e32 v109, v162, v109
	v_div_scale_f32 v162, vcc, v104, v105, v104
	v_mul_f32_e32 v163, v162, v109
	v_fma_f32 v166, -v108, v163, v162
	v_fmac_f32_e32 v163, v166, v109
	v_fma_f32 v108, -v108, v163, v162
	v_div_fmas_f32 v108, v108, v109, v163
	v_div_fixup_f32 v166, v108, v105, v104
	v_cvt_f32_f16_e32 v104, v227
	v_mul_f32_e32 v105, 0xbfb8aa3b, v104
	v_exp_f32_e32 v105, v105
	s_nop 0
	v_add_f32_e32 v105, 1.0, v105
	v_div_scale_f32 v108, s[8:9], v105, v105, v104
	v_rcp_f32_e32 v109, v108
	s_nop 0
	v_fma_f32 v162, -v108, v109, 1.0
	v_fmac_f32_e32 v109, v162, v109
	v_div_scale_f32 v162, vcc, v104, v105, v104
	v_mul_f32_e32 v163, v162, v109
	v_fma_f32 v167, -v108, v163, v162
	v_fmac_f32_e32 v163, v167, v109
	v_fma_f32 v108, -v108, v163, v162
	v_div_fmas_f32 v108, v108, v109, v163
	v_div_fixup_f32 v167, v108, v105, v104
	v_mov_b32_e32 v104, v111
	v_mov_b32_e32 v105, v107
	v_pk_mul_f32 v[104:105], v[104:105], v[104:105]
	v_mov_b32_e32 v108, v103
	v_mov_b32_e32 v109, v99
	v_pk_mul_f32 v[108:109], v[108:109], v[108:109]
	v_mov_b32_e32 v162, v104
	v_mov_b32_e32 v163, v100
	v_mov_b32_e32 v100, v105
	v_pk_add_f32 v[100:101], v[162:163], v[100:101]
	v_mov_b32_e32 v104, v108
	v_mov_b32_e32 v105, v96
	v_pk_add_f32 v[100:101], v[100:101], v[104:105]
	v_mov_b32_e32 v96, v109
	v_pk_add_f32 v[96:97], v[100:101], v[96:97]
	s_nop 1
	v_mov_b32_dpp v101, v97 quad_perm:[1,0,3,2] row_mask:0xf bank_mask:0xf bound_ctrl:1
	v_mov_b32_dpp v100, v96 quad_perm:[1,0,3,2] row_mask:0xf bank_mask:0xf bound_ctrl:1
	v_pk_add_f32 v[96:97], v[96:97], v[100:101]
	s_nop 1
	v_mov_b32_dpp v101, v97 quad_perm:[2,3,0,1] row_mask:0xf bank_mask:0xf bound_ctrl:1
	v_mov_b32_dpp v100, v96 quad_perm:[2,3,0,1] row_mask:0xf bank_mask:0xf bound_ctrl:1
	v_pk_add_f32 v[96:97], v[96:97], v[100:101]
	s_nop 1
	v_mov_b32_dpp v101, v97 row_ror:4 row_mask:0xf bank_mask:0xf bound_ctrl:1
	v_mov_b32_dpp v100, v96 row_ror:4 row_mask:0xf bank_mask:0xf bound_ctrl:1
	v_pk_add_f32 v[96:97], v[96:97], v[100:101]
	s_nop 1
	v_mov_b32_dpp v101, v97 row_ror:8 row_mask:0xf bank_mask:0xf bound_ctrl:1
	v_mov_b32_dpp v100, v96 row_ror:8 row_mask:0xf bank_mask:0xf bound_ctrl:1
	v_pk_add_f32 v[96:97], v[96:97], v[100:101]
	s_nop 0
	v_pk_fma_f32 v[96:97], v[96:97], s[0:1], v[170:171] op_sel_hi:[1,0,0]
	s_nop 0
	v_mul_f32_e32 v100, 0x4b800000, v97
	v_cmp_gt_f32_e64 s[8:9], s49, v97
	v_cmp_gt_f32_e32 vcc, s49, v96
	s_nop 0
	v_cndmask_b32_e64 v97, v97, v100, s[8:9]
	v_rsq_f32_e32 v97, v97
	s_nop 0
	v_mul_f32_e32 v100, 0x45800000, v97
	v_cndmask_b32_e64 v97, v97, v100, s[8:9]
	v_mul_f32_e32 v100, v110, v97
	v_mul_f32_e32 v100, v238, v100
	v_mul_f32_e32 v100, v164, v100
	v_med3_f32 v100, v100, s57, v194
	v_cvt_f16_f32_e32 v100, v100
	global_store_short v[160:161], v100, off
	v_mul_f32_e32 v100, v106, v97
	v_mul_f32_e32 v100, v237, v100
	v_mul_f32_e32 v100, v165, v100
	v_med3_f32 v100, v100, s57, v194
	v_cvt_f16_f32_e32 v100, v100
	global_store_short v[158:159], v100, off
	v_mul_f32_e32 v100, v102, v97
	v_mul_f32_e32 v97, v98, v97
	v_mul_f32_e32 v97, v235, v97
	v_mul_f32_e32 v97, v167, v97
	v_med3_f32 v97, v97, s57, v194
	v_cvt_f16_f32_e32 v97, v97
	v_mul_f32_e32 v100, v236, v100
	v_mul_f32_e32 v100, v166, v100
	v_med3_f32 v100, v100, s57, v194
	global_store_short v[154:155], v97, off
	v_mul_f32_e32 v97, 0x4b800000, v96
	v_cndmask_b32_e32 v96, v96, v97, vcc
	v_rsq_f32_e32 v96, v96
	v_cvt_f16_f32_e32 v100, v100
	v_mul_f32_e32 v97, 0x45800000, v96
	v_cndmask_b32_e32 v96, v96, v97, vcc
	v_cvt_f32_f16_e32 v97, v226
	global_store_short v[156:157], v100, off
	v_mul_f32_e32 v98, v111, v96
	v_mul_f32_e32 v98, v238, v98
	v_mul_f32_e32 v100, 0xbfb8aa3b, v97
	v_exp_f32_e32 v100, v100
	s_nop 0
	v_add_f32_e32 v100, 1.0, v100
	v_div_scale_f32 v101, s[8:9], v100, v100, v97
	v_rcp_f32_e32 v102, v101
	s_nop 0
	v_fma_f32 v104, -v101, v102, 1.0
	v_fmac_f32_e32 v102, v104, v102
	v_div_scale_f32 v104, vcc, v97, v100, v97
	v_mul_f32_e32 v105, v104, v102
	v_fma_f32 v106, -v101, v105, v104
	v_fmac_f32_e32 v105, v106, v102
	v_fma_f32 v101, -v101, v105, v104
	v_div_fmas_f32 v101, v101, v102, v105
	v_div_fixup_f32 v97, v101, v100, v97
	v_mul_f32_e32 v97, v97, v98
	v_med3_f32 v97, v97, s57, v194
	v_cvt_f16_f32_e32 v97, v97
	v_mul_f32_e32 v98, v107, v96
	v_mul_f32_e32 v98, v237, v98
	global_store_short v[152:153], v97, off
	v_cvt_f32_f16_e32 v97, v225
	v_mul_f32_e32 v100, 0xbfb8aa3b, v97
	v_exp_f32_e32 v100, v100
	s_nop 0
	v_add_f32_e32 v100, 1.0, v100
	v_div_scale_f32 v101, s[8:9], v100, v100, v97
	v_rcp_f32_e32 v102, v101
	s_nop 0
	v_fma_f32 v104, -v101, v102, 1.0
	v_fmac_f32_e32 v102, v104, v102
	v_div_scale_f32 v104, vcc, v97, v100, v97
	v_mul_f32_e32 v105, v104, v102
	v_fma_f32 v106, -v101, v105, v104
	v_fmac_f32_e32 v105, v106, v102
	v_fma_f32 v101, -v101, v105, v104
	v_div_fmas_f32 v101, v101, v102, v105
	v_div_fixup_f32 v97, v101, v100, v97
	v_mul_f32_e32 v97, v97, v98
	v_med3_f32 v97, v97, s57, v194
	v_cvt_f16_f32_e32 v97, v97
	v_mul_f32_e32 v98, v103, v96
	v_mul_f32_e32 v98, v236, v98
	v_mul_f32_e32 v96, v99, v96
	global_store_short v[150:151], v97, off
	v_cvt_f32_f16_e32 v97, v224
	v_mul_f32_e32 v96, v235, v96
	v_mul_f32_e32 v100, 0xbfb8aa3b, v97
	v_exp_f32_e32 v100, v100
	s_nop 0
	v_add_f32_e32 v100, 1.0, v100
	v_div_scale_f32 v101, s[8:9], v100, v100, v97
	v_rcp_f32_e32 v102, v101
	s_nop 0
	v_fma_f32 v103, -v101, v102, 1.0
	v_fmac_f32_e32 v102, v103, v102
	v_div_scale_f32 v103, vcc, v97, v100, v97
	v_mul_f32_e32 v104, v103, v102
	v_fma_f32 v105, -v101, v104, v103
	v_fmac_f32_e32 v104, v105, v102
	v_fma_f32 v101, -v101, v104, v103
	v_div_fmas_f32 v101, v101, v102, v104
	v_div_fixup_f32 v97, v101, v100, v97
	v_mul_f32_e32 v97, v97, v98
	v_med3_f32 v97, v97, s57, v194
	v_cvt_f16_f32_e32 v97, v97
	global_store_short v[148:149], v97, off
	v_cvt_f32_f16_e32 v97, v223
	v_mul_f32_e32 v98, 0xbfb8aa3b, v97
	v_exp_f32_e32 v98, v98
	s_nop 0
	v_add_f32_e32 v98, 1.0, v98
	v_div_scale_f32 v99, s[8:9], v98, v98, v97
	v_rcp_f32_e32 v100, v99
	s_nop 0
	v_fma_f32 v101, -v99, v100, 1.0
	v_fmac_f32_e32 v100, v101, v100
	v_div_scale_f32 v101, vcc, v97, v98, v97
	v_mul_f32_e32 v102, v101, v100
	v_fma_f32 v103, -v99, v102, v101
	v_fmac_f32_e32 v102, v103, v100
	v_fma_f32 v99, -v99, v102, v101
	v_div_fmas_f32 v99, v99, v100, v102
	v_div_fixup_f32 v97, v99, v98, v97
	v_mul_f32_e32 v96, v97, v96
	v_med3_f32 v96, v96, s57, v194
	v_cvt_f16_f32_e32 v96, v96
	s_andn2_b64 vcc, exec, s[10:11]
	global_store_short v[146:147], v96, off
	ds_read_b128 v[96:99], v116 offset:55296
	ds_read_b128 v[240:243], v117 offset:36864
	ds_read_b128 v[244:247], v117 offset:39168
	ds_read_b128 v[252:255], v117 offset:41472
	s_waitcnt lgkmcnt(2)
	v_pk_mul_f32 v[82:83], v[82:83], v[112:113] op_sel_hi:[1,0]
	v_mul_f32_e64 v80, v80, v112
	v_mul_f32_e64 v81, v81, v112
	v_pk_mul_f32 v[86:87], v[86:87], v[112:113] op_sel_hi:[1,0]
	v_pk_mul_f32 v[84:85], v[84:85], v[112:113] op_sel_hi:[1,0]
	v_mul_f32_e64 v90, v90, v112
	v_mul_f32_e64 v91, v91, v112
	v_pk_mul_f32 v[88:89], v[88:89], v[112:113] op_sel_hi:[1,0]
	v_pk_mul_f32 v[94:95], v[94:95], v[112:113] op_sel_hi:[1,0]
	v_pk_mul_f32 v[92:93], v[92:93], v[112:113] op_sel_hi:[1,0]
	s_nop 1
	v_mfma_f32_16x16x32_f16 v[80:83], v[96:99], v[240:243], v[80:83]
	ds_read_b128 v[240:243], v117 offset:43776
	ds_read_b128 v[100:103], v116 offset:55360
	s_waitcnt lgkmcnt(3)
	v_mfma_f32_16x16x32_f16 v[84:87], v[96:99], v[244:247], v[84:87]
	ds_read_b128 v[244:247], v117 offset:36928
	s_waitcnt lgkmcnt(3)
	v_mfma_f32_16x16x32_f16 v[88:91], v[96:99], v[252:255], v[88:91]
	ds_read_b128 v[252:255], v117 offset:39232
	s_waitcnt lgkmcnt(3)
	v_mfma_f32_16x16x32_f16 v[92:95], v[96:99], v[240:243], v[92:95]
	ds_read_b128 v[240:243], v117 offset:41536
	s_waitcnt lgkmcnt(2)
	v_mfma_f32_16x16x32_f16 v[80:83], v[100:103], v[244:247], v[80:83]
	ds_read_b128 v[244:247], v117 offset:43840
	s_waitcnt lgkmcnt(2)
	v_mfma_f32_16x16x32_f16 v[84:87], v[100:103], v[252:255], v[84:87]
	s_waitcnt lgkmcnt(1)
	v_mfma_f32_16x16x32_f16 v[88:91], v[100:103], v[240:243], v[88:91]
	s_waitcnt lgkmcnt(0)
	s_barrier
	v_mfma_f32_16x16x32_f16 v[92:95], v[100:103], v[244:247], v[92:95]
	v_med3_f32 v96, v80, s57, v194
	v_cvt_f16_f32_e32 v96, v96
	ds_write_b16 v215, v96 offset:46080
	v_med3_f32 v96, v81, s57, v194
	v_cvt_f16_f32_e32 v96, v96
	ds_write_b16 v215, v96 offset:46224
	v_med3_f32 v96, v82, s57, v194
	v_cvt_f16_f32_e32 v96, v96
	ds_write_b16 v215, v96 offset:46368
	v_med3_f32 v96, v83, s57, v194
	v_cvt_f16_f32_e32 v96, v96
	ds_write_b16 v215, v96 offset:46512
	v_med3_f32 v96, v84, s57, v194
	v_cvt_f16_f32_e32 v96, v96
	ds_write_b16 v215, v96 offset:46112
	v_med3_f32 v96, v85, s57, v194
	v_cvt_f16_f32_e32 v96, v96
	ds_write_b16 v216, v96 offset:46224
	v_med3_f32 v96, v86, s57, v194
	v_cvt_f16_f32_e32 v96, v96
	ds_write_b16 v216, v96 offset:46368
	v_med3_f32 v96, v87, s57, v194
	v_cvt_f16_f32_e32 v96, v96
	ds_write_b16 v216, v96 offset:46512
	v_med3_f32 v96, v88, s57, v194
	v_cvt_f16_f32_e32 v96, v96
	ds_write_b16 v215, v96 offset:46144
	v_med3_f32 v96, v89, s57, v194
	v_cvt_f16_f32_e32 v96, v96
	ds_write_b16 v217, v96 offset:46224
	v_med3_f32 v96, v90, s57, v194
	v_cvt_f16_f32_e32 v96, v96
	ds_write_b16 v217, v96 offset:46368
	v_med3_f32 v96, v91, s57, v194
	v_cvt_f16_f32_e32 v96, v96
	ds_write_b16 v217, v96 offset:46512
	v_med3_f32 v96, v92, s57, v194
	v_cvt_f16_f32_e32 v96, v96
	ds_write_b16 v215, v96 offset:46176
	v_med3_f32 v96, v93, s57, v194
	v_cvt_f16_f32_e32 v96, v96
	ds_write_b16 v218, v96 offset:46224
	v_med3_f32 v96, v94, s57, v194
	v_cvt_f16_f32_e32 v96, v96
	ds_write_b16 v218, v96 offset:46368
	v_med3_f32 v96, v95, s57, v194
	v_cvt_f16_f32_e32 v96, v96
	ds_write_b16 v218, v96 offset:46512
	s_cbranch_vccnz .LBB0_520
	ds_write_b128 v220, v[56:59]
	ds_write_b128 v211, v[60:63]
	ds_write_b128 v221, v[64:67]
	ds_write_b128 v212, v[68:71]
	ds_write_b128 v222, v[72:75]
	ds_write_b128 v213, v[76:79]
	s_branch .LBB0_520
